# v13 + memattn and dilated-attention S=K.Q^T sections: K-fragment LDS reads issued through a ring (8-deep / 4-deep) ahead of their MFMAs instead of read->wait->MFMA per fragment; row-max delayed one ti
# speedup vs baseline: 1.0087x; 1.0008x over previous
; #define LAS __attribute__((address_space(3)))
; #define MFMA16(a, b, c) __builtin_amdgcn_mfma_f32_16x16x32_bf16(a, b, c, 0, 0, 0)
; __device__ __forceinline__ AttnIdx attn_index(int P, int hw) {
;     ...
;     if (tq < 256) { X.m0 = (tq >> 7) * 8192; lt = tq & 127; S = 8192; } else { const int t = tq - 256; X.m0 = 16384 + (t >> 5) * 2048; lt = t & 31; S = 2048; }
; __device__ __forceinline__ void attn_phase(const Params& p, LAS unsigned char* lds, const int bx, const int G, const int tid) {
;     ...
;         const LAS unsigned char* kbp = L + AT_KS + (16 * wq + fr) * 144 + fq * 16;
;         const LAS unsigned char* vbp = L + AT_VT + (16 * wq + 4 * fq + (fr >> 2)) * 160 + (fr & 3) * 8;
; #pragma unroll
;         for (int j = 0; j < 9; ++j) { st[j] = (f32x4){0.f, 0.f, 0.f, 0.f};
;             const bf16x8 k0 = *(const LAS bf16x8*)(kbp + j * 2304), k1 = *(const LAS bf16x8*)(kbp + j * 2304 + 64);
;             st[j] = MFMA16(k0, q0, st[j]); st[j] = MFMA16(k1, q1, st[j]); }
;         st[9] = (f32x4){0.f, 0.f, 0.f, 0.f};
;         const int qi = 16 * wq + fr; float mx = -3e38f;
; #pragma unroll
;         for (int j = 0; j < 9; ++j)
; #pragma unroll
;             for (int e = 0; e < 4; ++e) { const int u = 16 * (wq + j) + 4 * fq + e, jk = X.nb * 64 - 64 + u, dl = u - 64 - qi; const bool ok = jk >= 0 && jk < X.n && dl >= -64 && dl <= 64;
;                 const float b = ((const LAS float*)(L + AT_BIAS))[ok ? dl + 64 : 0]; const float sv = ok ? st[j][e] + b : -1e30f; st[j][e] = sv; mx = fmaxf(mx, sv); }
.LBB0_407:
	ds_read_b32 v210, v127 offset:60928
	ds_read_b32 v211, v129 offset:60932
	ds_read_b32 v212, v129 offset:60936
	ds_read_b32 v213, v129 offset:60940
	ds_read_b32 v214, v129 offset:60992
	ds_read_b32 v215, v136 offset:60992
	ds_read_b32 v216, v138 offset:60992
	ds_read_b32 v217, v129 offset:61056
	ds_read_b32 v218, v136 offset:61056
	ds_read_b32 v219, v138 offset:61056
	ds_read_b32 v220, v129 offset:61120
	ds_read_b32 v221, v136 offset:61120
	ds_read_b32 v222, v138 offset:61120
	ds_read_b32 v223, v129 offset:61184
	ds_read_b32 v224, v129 offset:61196
	ds_read_b32 v225, v129 offset:61248
	ds_read_b32 v226, v138 offset:61248
	ds_read_b32 v227, v136 offset:61312
	ds_read_b32 v228, v138 offset:61312
	ds_read_b32 v229, v129 offset:61376
	ds_read_b32 v234, v138 offset:61376
	s_ashr_i32 s12, s86, 8
	s_and_b32 s37, s86, 0x1ff
	s_and_b32 s50, s12, -2
	s_cmpk_lt_u32 s37, 0x100
	s_cselect_b64 s[40:41], -1, 0
	v_add_u32_e32 v2, s50, v101
	s_and_b64 s[12:13], s[40:41], exec
	s_movk_i32 s2, 0x800
	v_ashrrev_i32_e32 v3, 1, v2
	s_cselect_b32 s12, 0x2000, s2
	v_and_b32_e32 v3, -2, v3
	v_lshrrev_b32_e64 v105, v3, s12
	v_lshrrev_b32_e32 v68, 6, v105
	v_add_u32_e32 v68, -1, v68
	s_cselect_b32 s56, 0x7f, 31
	v_mov_b32_e32 v69, s86
	v_bitop3_b32 v187, v68, s56, v69 bitop3:0x80
	v_cmp_ne_u32_e64 s[12:13], 0, v187
	ds_read_b128 v[236:239], v185
	ds_read_b128 v[246:249], v185 offset:64
	ds_read_b128 v[150:153], v185 offset:2304
	ds_read_b128 v[198:201], v185 offset:2368
	s_waitcnt lgkmcnt(3)
	v_mfma_f32_16x16x32_bf16 v[68:71], v[236:239], v[64:67], 0
	ds_read_b128 v[236:239], v185 offset:4608
	s_waitcnt lgkmcnt(3)
	v_mfma_f32_16x16x32_bf16 v[96:99], v[246:249], v[60:63], v[68:71]
	ds_read_b128 v[246:249], v185 offset:4672
	s_waitcnt lgkmcnt(3)
	v_mfma_f32_16x16x32_bf16 v[68:71], v[150:153], v[64:67], 0
	ds_read_b128 v[150:153], v185 offset:6912
	s_waitcnt lgkmcnt(3)
	v_mfma_f32_16x16x32_bf16 v[92:95], v[198:201], v[60:63], v[68:71]
	ds_read_b128 v[198:201], v185 offset:6976
	s_waitcnt lgkmcnt(3)
	v_mfma_f32_16x16x32_bf16 v[68:71], v[236:239], v[64:67], 0
	ds_read_b128 v[236:239], v185 offset:9216
	s_waitcnt lgkmcnt(3)
	v_mfma_f32_16x16x32_bf16 v[88:91], v[246:249], v[60:63], v[68:71]
	ds_read_b128 v[246:249], v185 offset:9280
	s_waitcnt lgkmcnt(3)
	v_mfma_f32_16x16x32_bf16 v[68:71], v[150:153], v[64:67], 0
	ds_read_b128 v[150:153], v185 offset:11520
	s_waitcnt lgkmcnt(3)
	v_mfma_f32_16x16x32_bf16 v[84:87], v[198:201], v[60:63], v[68:71]
	ds_read_b128 v[198:201], v185 offset:11584
	s_waitcnt lgkmcnt(3)
	v_mfma_f32_16x16x32_bf16 v[68:71], v[236:239], v[64:67], 0
	ds_read_b128 v[236:239], v185 offset:13824
	s_waitcnt lgkmcnt(3)
	v_mfma_f32_16x16x32_bf16 v[80:83], v[246:249], v[60:63], v[68:71]
	ds_read_b128 v[246:249], v185 offset:13888
	s_waitcnt lgkmcnt(3)
	v_mfma_f32_16x16x32_bf16 v[68:71], v[150:153], v[64:67], 0
	ds_read_b128 v[150:153], v185 offset:16128
	s_waitcnt lgkmcnt(3)
	v_mfma_f32_16x16x32_bf16 v[76:79], v[198:201], v[60:63], v[68:71]
	ds_read_b128 v[198:201], v185 offset:16192
	s_waitcnt lgkmcnt(3)
	v_mfma_f32_16x16x32_bf16 v[68:71], v[236:239], v[64:67], 0
	ds_read_b128 v[236:239], v185 offset:18432
	s_waitcnt lgkmcnt(3)
	v_mfma_f32_16x16x32_bf16 v[72:75], v[246:249], v[60:63], v[68:71]
	ds_read_b128 v[246:249], v185 offset:18496
	s_waitcnt lgkmcnt(3)
	v_mfma_f32_16x16x32_bf16 v[68:71], v[150:153], v[64:67], 0
	s_waitcnt lgkmcnt(2)
	v_mfma_f32_16x16x32_bf16 v[68:71], v[198:201], v[60:63], v[68:71]
	s_waitcnt lgkmcnt(1)
	v_mfma_f32_16x16x32_bf16 v[64:67], v[236:239], v[64:67], 0
	s_waitcnt lgkmcnt(0)
	v_mfma_f32_16x16x32_bf16 v[60:63], v[246:249], v[60:63], v[64:67]
	s_nop 5
	v_lshlrev_b32_e32 v64, 6, v187
	v_subrev_u32_e32 v107, 64, v64
	v_mov_b32_e32 v65, 0xf149f2ca
	v_mov_b32_e32 v66, 0xf149f2ca
	s_and_saveexec_b64 s[50:51], s[12:13]
	s_cbranch_execz .LBB0_411
	v_or_b32_e32 v66, v107, v126
	v_readlane_b32 s2, v254, 57
	v_cmp_lt_i32_e32 vcc, v66, v105
	v_readlane_b32 s3, v254, 58
	s_and_b64 s[58:59], vcc, s[2:3]
	v_mov_b32_e32 v66, 0xf149f2ca
	s_and_saveexec_b64 vcc, s[58:59]
	s_cbranch_execz .LBB0_410
	s_waitcnt lgkmcnt(0)
	v_add_f32_e32 v66, v96, v210

; #define LAS __attribute__((address_space(3)))
; #define MFMA16(a, b, c) __builtin_amdgcn_mfma_f32_16x16x32_bf16(a, b, c, 0, 0, 0)
; __device__ __forceinline__ void memattn_group(const Params& p, LAS unsigned char* lds, int grp, const int tid) {
;     ...
;         f32x4 st[16]; float mx = -3e38f;
; #pragma unroll
;         for (int ct = 0; ct < 16; ++ct) { st[ct] = (f32x4){0.f, 0.f, 0.f, 0.f};
; #pragma unroll
;             for (int ks = 0; ks < 4; ++ks) { const bf16x8 kb = *(const LAS bf16x8*)(lds + MA_KS + (16 * ct + fr) * 272 + (32 * ks + 8 * fq) * 2); st[ct] = MFMA16(kb, qa[ks], st[ct]); }
;             mx = fmaxf(fmaxf(mx, fmaxf(st[ct][0], st[ct][1])), fmaxf(st[ct][2], st[ct][3])); }
.LBB0_500:
	s_addk_i32 s5, 0x80
	s_cmpk_lg_i32 s5, 0x200
	ds_read_b128 v[198:201], v169
	ds_read_b128 v[202:205], v169 offset:64
	ds_read_b128 v[206:209], v169 offset:128
	ds_read_b128 v[210:213], v169 offset:192
	ds_read_b128 v[214:217], v169 offset:4352
	ds_read_b128 v[218:221], v169 offset:4416
	ds_read_b128 v[222:225], v169 offset:4480
	ds_read_b128 v[226:229], v169 offset:4544
	s_waitcnt lgkmcnt(7)
	v_mfma_f32_16x16x32_bf16 v[34:37], v[198:201], v[30:33], 0
	ds_read_b128 v[198:201], v169 offset:8704
	s_waitcnt lgkmcnt(7)
	v_mfma_f32_16x16x32_bf16 v[34:37], v[202:205], v[26:29], v[34:37]
	ds_read_b128 v[202:205], v169 offset:8768
	s_waitcnt lgkmcnt(7)
	v_mfma_f32_16x16x32_bf16 v[34:37], v[206:209], v[22:25], v[34:37]
	ds_read_b128 v[206:209], v169 offset:8832
	s_waitcnt lgkmcnt(7)
	v_mfma_f32_16x16x32_bf16 v[34:37], v[210:213], v[18:21], v[34:37]
	ds_read_b128 v[210:213], v169 offset:8896
	s_waitcnt lgkmcnt(7)
	v_mfma_f32_16x16x32_bf16 v[38:41], v[214:217], v[30:33], 0
	ds_read_b128 v[214:217], v169 offset:13056
	s_waitcnt lgkmcnt(7)
	v_mfma_f32_16x16x32_bf16 v[38:41], v[218:221], v[26:29], v[38:41]
	ds_read_b128 v[218:221], v169 offset:13120
	s_waitcnt lgkmcnt(7)
	v_mfma_f32_16x16x32_bf16 v[38:41], v[222:225], v[22:25], v[38:41]
	ds_read_b128 v[222:225], v169 offset:13184
	s_waitcnt lgkmcnt(7)
	v_mfma_f32_16x16x32_bf16 v[38:41], v[226:229], v[18:21], v[38:41]
	ds_read_b128 v[226:229], v169 offset:13248
	v_max_f32_e32 v234, v35, v35
	v_max_f32_e32 v235, v34, v34
	v_max_f32_e32 v234, v235, v234
	v_max_f32_e32 v235, v37, v37
	v_max_f32_e32 v236, v36, v36
	v_max_f32_e32 v235, v236, v235
	v_max3_f32 v237, v234, s12, v235
	s_waitcnt lgkmcnt(7)
	v_mfma_f32_16x16x32_bf16 v[42:45], v[198:201], v[30:33], 0
	ds_read_b128 v[198:201], v169 offset:17408
	s_waitcnt lgkmcnt(7)
	v_mfma_f32_16x16x32_bf16 v[42:45], v[202:205], v[26:29], v[42:45]
	ds_read_b128 v[202:205], v169 offset:17472
	s_waitcnt lgkmcnt(7)
	v_mfma_f32_16x16x32_bf16 v[42:45], v[206:209], v[22:25], v[42:45]
	ds_read_b128 v[206:209], v169 offset:17536
	s_waitcnt lgkmcnt(7)
	v_mfma_f32_16x16x32_bf16 v[42:45], v[210:213], v[18:21], v[42:45]
	ds_read_b128 v[210:213], v169 offset:17600
	v_max_f32_e32 v234, v39, v39
	v_max_f32_e32 v235, v38, v38
	v_max_f32_e32 v234, v235, v234
	v_max_f32_e32 v235, v41, v41
	v_max_f32_e32 v236, v40, v40
	v_max_f32_e32 v235, v236, v235
	v_max3_f32 v237, v237, v234, v235
	s_waitcnt lgkmcnt(7)
	v_mfma_f32_16x16x32_bf16 v[46:49], v[214:217], v[30:33], 0
	ds_read_b128 v[214:217], v169 offset:21760
	s_waitcnt lgkmcnt(7)
	v_mfma_f32_16x16x32_bf16 v[46:49], v[218:221], v[26:29], v[46:49]
	ds_read_b128 v[218:221], v169 offset:21824
	s_waitcnt lgkmcnt(7)
	v_mfma_f32_16x16x32_bf16 v[46:49], v[222:225], v[22:25], v[46:49]
	ds_read_b128 v[222:225], v169 offset:21888
	s_waitcnt lgkmcnt(7)
	v_mfma_f32_16x16x32_bf16 v[46:49], v[226:229], v[18:21], v[46:49]
	ds_read_b128 v[226:229], v169 offset:21952
	v_max_f32_e32 v234, v43, v43
	v_max_f32_e32 v235, v42, v42
	v_max_f32_e32 v234, v235, v234
	v_max_f32_e32 v235, v45, v45
	v_max_f32_e32 v236, v44, v44
	v_max_f32_e32 v235, v236, v235
	v_max3_f32 v237, v237, v234, v235
	s_waitcnt lgkmcnt(7)
	v_mfma_f32_16x16x32_bf16 v[50:53], v[198:201], v[30:33], 0
	ds_read_b128 v[198:201], v169 offset:26112
	s_waitcnt lgkmcnt(7)
	v_mfma_f32_16x16x32_bf16 v[50:53], v[202:205], v[26:29], v[50:53]
	ds_read_b128 v[202:205], v169 offset:26176
	s_waitcnt lgkmcnt(7)
	v_mfma_f32_16x16x32_bf16 v[50:53], v[206:209], v[22:25], v[50:53]
	ds_read_b128 v[206:209], v169 offset:26240
	s_waitcnt lgkmcnt(7)
	v_mfma_f32_16x16x32_bf16 v[50:53], v[210:213], v[18:21], v[50:53]
	ds_read_b128 v[210:213], v169 offset:26304
	v_max_f32_e32 v234, v47, v47
	v_max_f32_e32 v235, v46, v46
	v_max_f32_e32 v234, v235, v234
	v_max_f32_e32 v235, v49, v49
	v_max_f32_e32 v236, v48, v48
	v_max_f32_e32 v235, v236, v235
	v_max3_f32 v237, v237, v234, v235
	s_waitcnt lgkmcnt(7)
	v_mfma_f32_16x16x32_bf16 v[54:57], v[214:217], v[30:33], 0
	ds_read_b128 v[214:217], v169 offset:30464
	s_waitcnt lgkmcnt(7)
	v_mfma_f32_16x16x32_bf16 v[54:57], v[218:221], v[26:29], v[54:57]
	ds_read_b128 v[218:221], v169 offset:30528
	s_waitcnt lgkmcnt(7)
	v_mfma_f32_16x16x32_bf16 v[54:57], v[222:225], v[22:25], v[54:57]
	ds_read_b128 v[222:225], v169 offset:30592
	s_waitcnt lgkmcnt(7)
	v_mfma_f32_16x16x32_bf16 v[54:57], v[226:229], v[18:21], v[54:57]
	ds_read_b128 v[226:229], v169 offset:30656
	v_max_f32_e32 v234, v51, v51
	v_max_f32_e32 v235, v50, v50
	v_max_f32_e32 v234, v235, v234
	v_max_f32_e32 v235, v53, v53
	v_max_f32_e32 v236, v52, v52
	v_max_f32_e32 v235, v236, v235
	v_max3_f32 v237, v237, v234, v235
	s_waitcnt lgkmcnt(7)
	v_mfma_f32_16x16x32_bf16 v[58:61], v[198:201], v[30:33], 0
	ds_read_b128 v[198:201], v169 offset:34816
	s_waitcnt lgkmcnt(7)
	v_mfma_f32_16x16x32_bf16 v[58:61], v[202:205], v[26:29], v[58:61]
	ds_read_b128 v[202:205], v169 offset:34880
	s_waitcnt lgkmcnt(7)
	v_mfma_f32_16x16x32_bf16 v[58:61], v[206:209], v[22:25], v[58:61]
	ds_read_b128 v[206:209], v169 offset:34944
	s_waitcnt lgkmcnt(7)
	v_mfma_f32_16x16x32_bf16 v[58:61], v[210:213], v[18:21], v[58:61]
	ds_read_b128 v[210:213], v169 offset:35008
	v_max_f32_e32 v234, v55, v55
	v_max_f32_e32 v235, v54, v54
	v_max_f32_e32 v234, v235, v234
	v_max_f32_e32 v235, v57, v57
	v_max_f32_e32 v236, v56, v56
	v_max_f32_e32 v235, v236, v235
	v_max3_f32 v237, v237, v234, v235
	s_waitcnt lgkmcnt(7)
	v_mfma_f32_16x16x32_bf16 v[62:65], v[214:217], v[30:33], 0
	ds_read_b128 v[214:217], v169 offset:39168
	s_waitcnt lgkmcnt(7)
	v_mfma_f32_16x16x32_bf16 v[62:65], v[218:221], v[26:29], v[62:65]
	ds_read_b128 v[218:221], v169 offset:39232
	s_waitcnt lgkmcnt(7)
; #define LAS __attribute__((address_space(3)))
; #define MFMA16(a, b, c) __builtin_amdgcn_mfma_f32_16x16x32_bf16(a, b, c, 0, 0, 0)
; __device__ __forceinline__ void memattn_group(const Params& p, LAS unsigned char* lds, int grp, const int tid) {
;     ...
;         f32x4 st[16]; float mx = -3e38f;
; #pragma unroll
;         for (int ct = 0; ct < 16; ++ct) { st[ct] = (f32x4){0.f, 0.f, 0.f, 0.f};
; #pragma unroll
;             for (int ks = 0; ks < 4; ++ks) { const bf16x8 kb = *(const LAS bf16x8*)(lds + MA_KS + (16 * ct + fr) * 272 + (32 * ks + 8 * fq) * 2); st[ct] = MFMA16(kb, qa[ks], st[ct]); }
;             mx = fmaxf(fmaxf(mx, fmaxf(st[ct][0], st[ct][1])), fmaxf(st[ct][2], st[ct][3])); }
	v_mfma_f32_16x16x32_bf16 v[62:65], v[222:225], v[22:25], v[62:65]
	ds_read_b128 v[222:225], v169 offset:39296
	s_waitcnt lgkmcnt(7)
	v_mfma_f32_16x16x32_bf16 v[62:65], v[226:229], v[18:21], v[62:65]
	ds_read_b128 v[226:229], v169 offset:39360
	v_max_f32_e32 v234, v59, v59
	v_max_f32_e32 v235, v58, v58
	v_max_f32_e32 v234, v235, v234
	v_max_f32_e32 v235, v61, v61
	v_max_f32_e32 v236, v60, v60
	v_max_f32_e32 v235, v236, v235
	v_max3_f32 v237, v237, v234, v235
	s_waitcnt lgkmcnt(7)
	v_mfma_f32_16x16x32_bf16 v[66:69], v[198:201], v[30:33], 0
	ds_read_b128 v[198:201], v169 offset:43520
	s_waitcnt lgkmcnt(7)
	v_mfma_f32_16x16x32_bf16 v[66:69], v[202:205], v[26:29], v[66:69]
	ds_read_b128 v[202:205], v169 offset:43584
	s_waitcnt lgkmcnt(7)
	v_mfma_f32_16x16x32_bf16 v[66:69], v[206:209], v[22:25], v[66:69]
	ds_read_b128 v[206:209], v169 offset:43648
	s_waitcnt lgkmcnt(7)
	v_mfma_f32_16x16x32_bf16 v[66:69], v[210:213], v[18:21], v[66:69]
	ds_read_b128 v[210:213], v169 offset:43712
	v_max_f32_e32 v234, v63, v63
	v_max_f32_e32 v235, v62, v62
	v_max_f32_e32 v234, v235, v234
	v_max_f32_e32 v235, v65, v65
	v_max_f32_e32 v236, v64, v64
	v_max_f32_e32 v235, v236, v235
	v_max3_f32 v237, v237, v234, v235
	s_waitcnt lgkmcnt(7)
	v_mfma_f32_16x16x32_bf16 v[70:73], v[214:217], v[30:33], 0
	ds_read_b128 v[214:217], v169 offset:47872
	s_waitcnt lgkmcnt(7)
	v_mfma_f32_16x16x32_bf16 v[70:73], v[218:221], v[26:29], v[70:73]
	ds_read_b128 v[218:221], v169 offset:47936
	s_waitcnt lgkmcnt(7)
	v_mfma_f32_16x16x32_bf16 v[70:73], v[222:225], v[22:25], v[70:73]
	ds_read_b128 v[222:225], v169 offset:48000
	s_waitcnt lgkmcnt(7)
	v_mfma_f32_16x16x32_bf16 v[70:73], v[226:229], v[18:21], v[70:73]
	ds_read_b128 v[226:229], v169 offset:48064
	v_max_f32_e32 v234, v67, v67
	v_max_f32_e32 v235, v66, v66
	v_max_f32_e32 v234, v235, v234
	v_max_f32_e32 v235, v69, v69
	v_max_f32_e32 v236, v68, v68
	v_max_f32_e32 v235, v236, v235
	v_max3_f32 v237, v237, v234, v235
	s_waitcnt lgkmcnt(7)
	v_mfma_f32_16x16x32_bf16 v[74:77], v[198:201], v[30:33], 0
	ds_read_b128 v[198:201], v169 offset:52224
	s_waitcnt lgkmcnt(7)
	v_mfma_f32_16x16x32_bf16 v[74:77], v[202:205], v[26:29], v[74:77]
	ds_read_b128 v[202:205], v169 offset:52288
	s_waitcnt lgkmcnt(7)
	v_mfma_f32_16x16x32_bf16 v[74:77], v[206:209], v[22:25], v[74:77]
	ds_read_b128 v[206:209], v169 offset:52352
	s_waitcnt lgkmcnt(7)
	v_mfma_f32_16x16x32_bf16 v[74:77], v[210:213], v[18:21], v[74:77]
	ds_read_b128 v[210:213], v169 offset:52416
	v_max_f32_e32 v234, v71, v71
	v_max_f32_e32 v235, v70, v70
	v_max_f32_e32 v234, v235, v234
	v_max_f32_e32 v235, v73, v73
	v_max_f32_e32 v236, v72, v72
	v_max_f32_e32 v235, v236, v235
	v_max3_f32 v237, v237, v234, v235
	s_waitcnt lgkmcnt(7)
	v_mfma_f32_16x16x32_bf16 v[78:81], v[214:217], v[30:33], 0
	ds_read_b128 v[214:217], v169 offset:56576
	s_waitcnt lgkmcnt(7)
	v_mfma_f32_16x16x32_bf16 v[78:81], v[218:221], v[26:29], v[78:81]
	ds_read_b128 v[218:221], v169 offset:56640
	s_waitcnt lgkmcnt(7)
	v_mfma_f32_16x16x32_bf16 v[78:81], v[222:225], v[22:25], v[78:81]
	ds_read_b128 v[222:225], v169 offset:56704
	s_waitcnt lgkmcnt(7)
	v_mfma_f32_16x16x32_bf16 v[78:81], v[226:229], v[18:21], v[78:81]
	ds_read_b128 v[226:229], v169 offset:56768
	v_max_f32_e32 v234, v75, v75
	v_max_f32_e32 v235, v74, v74
	v_max_f32_e32 v234, v235, v234
	v_max_f32_e32 v235, v77, v77
	v_max_f32_e32 v236, v76, v76
	v_max_f32_e32 v235, v236, v235
	v_max3_f32 v237, v237, v234, v235
	s_waitcnt lgkmcnt(7)
	v_mfma_f32_16x16x32_bf16 v[82:85], v[198:201], v[30:33], 0
	ds_read_b128 v[198:201], v169 offset:60928
	s_waitcnt lgkmcnt(7)
	v_mfma_f32_16x16x32_bf16 v[82:85], v[202:205], v[26:29], v[82:85]
	ds_read_b128 v[202:205], v169 offset:60992
	s_waitcnt lgkmcnt(7)
	v_mfma_f32_16x16x32_bf16 v[82:85], v[206:209], v[22:25], v[82:85]
	ds_read_b128 v[206:209], v169 offset:61056
	s_waitcnt lgkmcnt(7)
	v_mfma_f32_16x16x32_bf16 v[82:85], v[210:213], v[18:21], v[82:85]
	ds_read_b128 v[210:213], v169 offset:61120
	v_max_f32_e32 v234, v79, v79
	v_max_f32_e32 v235, v78, v78
	v_max_f32_e32 v234, v235, v234
	v_max_f32_e32 v235, v81, v81
	v_max_f32_e32 v236, v80, v80
	v_max_f32_e32 v235, v236, v235
	v_max3_f32 v237, v237, v234, v235
	s_waitcnt lgkmcnt(7)
	v_mfma_f32_16x16x32_bf16 v[86:89], v[214:217], v[30:33], 0
	ds_read_b128 v[214:217], v169 offset:65280
	s_waitcnt lgkmcnt(7)
	v_mfma_f32_16x16x32_bf16 v[86:89], v[218:221], v[26:29], v[86:89]
	ds_read_b128 v[218:221], v169 offset:65344
	s_waitcnt lgkmcnt(7)
	v_mfma_f32_16x16x32_bf16 v[86:89], v[222:225], v[22:25], v[86:89]
	ds_read_b128 v[222:225], v169 offset:65408
	s_waitcnt lgkmcnt(7)
	v_mfma_f32_16x16x32_bf16 v[86:89], v[226:229], v[18:21], v[86:89]
	ds_read_b128 v[226:229], v169 offset:65472
	v_max_f32_e32 v234, v83, v83
	v_max_f32_e32 v235, v82, v82
	v_max_f32_e32 v234, v235, v234
	v_max_f32_e32 v235, v85, v85
	v_max_f32_e32 v236, v84, v84
	v_max_f32_e32 v235, v236, v235
	v_max3_f32 v237, v237, v234, v235
	s_waitcnt lgkmcnt(7)
	v_mfma_f32_16x16x32_bf16 v[90:93], v[198:201], v[30:33], 0
	s_waitcnt lgkmcnt(6)
	v_mfma_f32_16x16x32_bf16 v[90:93], v[202:205], v[26:29], v[90:93]
	s_waitcnt lgkmcnt(5)
	v_mfma_f32_16x16x32_bf16 v[90:93], v[206:209], v[22:25], v[90:93]
	s_waitcnt lgkmcnt(4)
	v_mfma_f32_16x16x32_bf16 v[90:93], v[210:213], v[18:21], v[90:93]
	v_max_f32_e32 v234, v87, v87
	v_max_f32_e32 v235, v86, v86
	v_max_f32_e32 v234, v235, v234
	v_max_f32_e32 v235, v89, v89
	v_max_f32_e32 v236, v88, v88
	v_max_f32_e32 v235, v236, v235
	v_max3_f32 v237, v237, v234, v235
	s_waitcnt lgkmcnt(3)
	v_mfma_f32_16x16x32_bf16 v[30:33], v[214:217], v[30:33], 0
	s_waitcnt lgkmcnt(2)
; #define LAS __attribute__((address_space(3)))
; #define MFMA16(a, b, c) __builtin_amdgcn_mfma_f32_16x16x32_bf16(a, b, c, 0, 0, 0)
; __device__ __forceinline__ void memattn_group(const Params& p, LAS unsigned char* lds, int grp, const int tid) {
;     ...
;         for (int ct = 0; ct < 16; ++ct) { st[ct] = (f32x4){0.f, 0.f, 0.f, 0.f};
; #pragma unroll
;             for (int ks = 0; ks < 4; ++ks) { const bf16x8 kb = *(const LAS bf16x8*)(lds + MA_KS + (16 * ct + fr) * 272 + (32 * ks + 8 * fq) * 2); st[ct] = MFMA16(kb, qa[ks], st[ct]); }
;             mx = fmaxf(fmaxf(mx, fmaxf(st[ct][0], st[ct][1])), fmaxf(st[ct][2], st[ct][3])); }
;         mx = fmaxf(mx, __shfl_xor(mx, 16)); mx = fmaxf(mx, __shfl_xor(mx, 32));
;         float sm = 0.f;
; #pragma unroll
;         for (int ct = 0; ct < 16; ++ct)
; #pragma unroll
;             for (int e = 0; e < 4; ++e) { const float pv = __expf(st[ct][e] - mx); st[ct][e] = pv; sm += pv; }
	v_mfma_f32_16x16x32_bf16 v[26:29], v[218:221], v[26:29], v[30:33]
	s_waitcnt lgkmcnt(1)
	v_mfma_f32_16x16x32_bf16 v[22:25], v[222:225], v[22:25], v[26:29]
	s_waitcnt lgkmcnt(0)
	v_mfma_f32_16x16x32_bf16 v[18:21], v[226:229], v[18:21], v[22:25]
	v_max_f32_e32 v234, v91, v91
	v_max_f32_e32 v235, v90, v90
	v_max_f32_e32 v234, v235, v234
	v_max_f32_e32 v235, v93, v93
	v_max_f32_e32 v236, v92, v92
	v_max_f32_e32 v235, v236, v235
	v_max3_f32 v237, v237, v234, v235
	s_nop 7
	v_max_f32_e32 v234, v19, v19
	v_max_f32_e32 v235, v18, v18
	v_max_f32_e32 v234, v235, v234
	v_max_f32_e32 v235, v21, v21
	v_max_f32_e32 v236, v20, v20
	v_max_f32_e32 v235, v236, v235
	v_and_b32_e32 v24, 64, v231
	v_max3_f32 v22, v237, v234, v235
	v_xor_b32_e32 v23, 16, v231
	v_add_u32_e32 v24, 64, v24
	v_cmp_lt_i32_e32 vcc, v23, v24
	s_nop 1
	v_cndmask_b32_e32 v23, v231, v23, vcc
	v_lshlrev_b32_e32 v26, 2, v23
	ds_bpermute_b32 v23, v26, v22
	s_waitcnt lgkmcnt(0)
	v_max_f32_e32 v23, v23, v23
	v_max_f32_e32 v22, v22, v23
	v_xor_b32_e32 v23, 32, v231
	v_cmp_lt_i32_e32 vcc, v23, v24
	s_nop 1
	v_cndmask_b32_e32 v23, v231, v23, vcc
	v_lshlrev_b32_e32 v27, 2, v23
	ds_bpermute_b32 v23, v27, v22
	s_waitcnt lgkmcnt(0)
	v_max_f32_e32 v23, v23, v23
	v_max_f32_e32 v150, v22, v23
	v_sub_f32_e32 v23, v35, v150
	v_mul_f32_e32 v23, 0x3fb8aa3b, v23
	v_exp_f32_e32 v185, v23
	v_sub_f32_e32 v23, v36, v150
	v_mul_f32_e32 v23, 0x3fb8aa3b, v23
	v_exp_f32_e32 v184, v23
	v_sub_f32_e32 v23, v37, v150
	v_mul_f32_e32 v23, 0x3fb8aa3b, v23
	v_exp_f32_e32 v186, v23
	v_sub_f32_e32 v23, v38, v150
	v_mul_f32_e32 v23, 0x3fb8aa3b, v23
	v_exp_f32_e32 v187, v23
	v_sub_f32_e32 v23, v39, v150
	v_mul_f32_e32 v23, 0x3fb8aa3b, v23
	v_exp_f32_e32 v188, v23
	v_sub_f32_e32 v23, v40, v150
	v_mul_f32_e32 v23, 0x3fb8aa3b, v23
	v_exp_f32_e32 v190, v23
	v_sub_f32_e32 v23, v41, v150
	v_mul_f32_e32 v23, 0x3fb8aa3b, v23
	v_exp_f32_e32 v191, v23
	v_sub_f32_e32 v23, v42, v150
	v_mul_f32_e32 v23, 0x3fb8aa3b, v23
	v_exp_f32_e32 v175, v23
	v_sub_f32_e32 v23, v43, v150
	v_mul_f32_e32 v23, 0x3fb8aa3b, v23
	v_exp_f32_e32 v176, v23
	v_sub_f32_e32 v23, v44, v150
	v_mul_f32_e32 v23, 0x3fb8aa3b, v23
	v_exp_f32_e32 v177, v23
	v_sub_f32_e32 v23, v45, v150
	v_mul_f32_e32 v23, 0x3fb8aa3b, v23
	v_exp_f32_e32 v178, v23
	v_sub_f32_e32 v23, v46, v150
	v_mul_f32_e32 v23, 0x3fb8aa3b, v23
	v_exp_f32_e32 v179, v23
	v_sub_f32_e32 v23, v47, v150
	v_mul_f32_e32 v23, 0x3fb8aa3b, v23
	v_exp_f32_e32 v180, v23
	v_sub_f32_e32 v23, v48, v150
	v_mul_f32_e32 v23, 0x3fb8aa3b, v23
	v_exp_f32_e32 v181, v23
	v_sub_f32_e32 v23, v49, v150
	v_mul_f32_e32 v23, 0x3fb8aa3b, v23
	v_exp_f32_e32 v182, v23
	v_sub_f32_e32 v23, v50, v150
	v_mul_f32_e32 v23, 0x3fb8aa3b, v23
	v_exp_f32_e32 v115, v23
	v_sub_f32_e32 v23, v51, v150
	v_mul_f32_e32 v23, 0x3fb8aa3b, v23
	v_exp_f32_e32 v117, v23
	v_sub_f32_e32 v23, v52, v150
	v_mul_f32_e32 v23, 0x3fb8aa3b, v23
	v_exp_f32_e32 v123, v23
	v_sub_f32_e32 v23, v53, v150
	v_mul_f32_e32 v23, 0x3fb8aa3b, v23
	v_exp_f32_e32 v170, v23
	v_sub_f32_e32 v23, v54, v150
	v_mul_f32_e32 v23, 0x3fb8aa3b, v23
	v_exp_f32_e32 v171, v23
	v_sub_f32_e32 v23, v55, v150
	v_mul_f32_e32 v23, 0x3fb8aa3b, v23
	v_exp_f32_e32 v172, v23
	v_sub_f32_e32 v23, v56, v150
	v_mul_f32_e32 v23, 0x3fb8aa3b, v23
	v_exp_f32_e32 v173, v23
	v_sub_f32_e32 v23, v57, v150
	v_sub_f32_e32 v22, v34, v150
	v_mul_f32_e32 v23, 0x3fb8aa3b, v23
	v_mul_f32_e32 v22, 0x3fb8aa3b, v22
	v_exp_f32_e32 v174, v23
	v_sub_f32_e32 v23, v58, v150
	v_exp_f32_e32 v183, v22
	v_mul_f32_e32 v23, 0x3fb8aa3b, v23
	v_exp_f32_e32 v56, v23
	v_sub_f32_e32 v23, v59, v150
	v_mul_f32_e32 v23, 0x3fb8aa3b, v23
	v_exp_f32_e32 v57, v23
	v_sub_f32_e32 v23, v60, v150
	v_add_f32_e32 v22, 0, v183
	v_mul_f32_e32 v23, 0x3fb8aa3b, v23
	v_add_f32_e32 v22, v185, v22
	v_exp_f32_e32 v58, v23
	v_sub_f32_e32 v23, v61, v150
	v_add_f32_e32 v22, v184, v22
	v_mul_f32_e32 v23, 0x3fb8aa3b, v23
	v_add_f32_e32 v22, v186, v22
	v_exp_f32_e32 v59, v23
	v_sub_f32_e32 v23, v62, v150
	v_add_f32_e32 v22, v187, v22
	v_mul_f32_e32 v23, 0x3fb8aa3b, v23
	v_add_f32_e32 v22, v188, v22
	v_exp_f32_e32 v60, v23
	v_sub_f32_e32 v23, v63, v150
	v_add_f32_e32 v22, v190, v22
	v_mul_f32_e32 v23, 0x3fb8aa3b, v23
	v_add_f32_e32 v22, v191, v22
	v_exp_f32_e32 v61, v23
	v_sub_f32_e32 v23, v64, v150
	v_add_f32_e32 v22, v175, v22
	v_mul_f32_e32 v23, 0x3fb8aa3b, v23
	v_add_f32_e32 v22, v176, v22
	v_exp_f32_e32 v62, v23
	v_sub_f32_e32 v23, v65, v150
	v_add_f32_e32 v22, v177, v22
	v_mul_f32_e32 v23, 0x3fb8aa3b, v23
	v_add_f32_e32 v22, v178, v22
	v_exp_f32_e32 v63, v23
	v_sub_f32_e32 v23, v66, v150
	v_add_f32_e32 v22, v179, v22
	v_mul_f32_e32 v23, 0x3fb8aa3b, v23
	v_add_f32_e32 v22, v180, v22
	v_exp_f32_e32 v48, v23
	v_sub_f32_e32 v23, v67, v150
	v_add_f32_e32 v22, v181, v22
	v_mul_f32_e32 v23, 0x3fb8aa3b, v23
	v_add_f32_e32 v22, v182, v22
	v_exp_f32_e32 v49, v23
	v_sub_f32_e32 v23, v68, v150
	v_add_f32_e32 v22, v115, v22
	v_mul_f32_e32 v23, 0x3fb8aa3b, v23
	v_add_f32_e32 v22, v117, v22
	v_exp_f32_e32 v50, v23
	v_sub_f32_e32 v23, v69, v150
	v_add_f32_e32 v22, v123, v22
	v_mul_f32_e32 v23, 0x3fb8aa3b, v23
	v_add_f32_e32 v22, v170, v22
	v_exp_f32_e32 v52, v23
	v_sub_f32_e32 v23, v70, v150
	v_add_f32_e32 v22, v171, v22
	v_mul_f32_e32 v23, 0x3fb8aa3b, v23
	v_add_f32_e32 v22, v172, v22
	v_exp_f32_e32 v51, v23
	v_sub_f32_e32 v23, v71, v150
	v_add_f32_e32 v22, v173, v22
	v_mul_f32_e32 v23, 0x3fb8aa3b, v23
	v_add_f32_e32 v22, v174, v22
	v_exp_f32_e32 v54, v23
	v_sub_f32_e32 v23, v72, v150
	v_add_f32_e32 v22, v56, v22
	v_mul_f32_e32 v23, 0x3fb8aa3b, v23
	v_add_f32_e32 v22, v57, v22
	v_exp_f32_e32 v53, v23
	v_sub_f32_e32 v23, v73, v150
	v_add_f32_e32 v22, v58, v22
	v_mul_f32_e32 v23, 0x3fb8aa3b, v23
; #define LAS __attribute__((address_space(3)))
; __device__ __forceinline__ unsigned pk2(float lo, float hi) { return f2bf(lo) | (f2bf(hi) << 16); }
; #define MFMA16(a, b, c) __builtin_amdgcn_mfma_f32_16x16x32_bf16(a, b, c, 0, 0, 0)
; __device__ __forceinline__ v4i16_t vtr(const LAS unsigned char* p) { return __builtin_amdgcn_ds_read_tr16_b64_v4i16((LAS v4i16_t*)p); }
; __device__ __forceinline__ void memattn_group(const Params& p, LAS unsigned char* lds, int grp, const int tid) {
;     ...
;         float sm = 0.f;
; #pragma unroll
;         for (int ct = 0; ct < 16; ++ct)
; #pragma unroll
;             for (int e = 0; e < 4; ++e) { const float pv = __expf(st[ct][e] - mx); st[ct][e] = pv; sm += pv; }
;         sm += __shfl_xor(sm, 16); sm += __shfl_xor(sm, 32);
;         f32x4 ot[8];
; #pragma unroll
;         for (int dt = 0; dt < 8; ++dt) ot[dt] = (f32x4){0.f, 0.f, 0.f, 0.f};
; #pragma unroll
;         for (int ks = 0; ks < 8; ++ks) { v4u pw; pw.x = pk2(st[2 * ks][0], st[2 * ks][1]); pw.y = pk2(st[2 * ks][2], st[2 * ks][3]); pw.z = pk2(st[2 * ks + 1][0], st[2 * ks + 1][1]); pw.w = pk2(st[2 * ks + 1][2], st[2 * ks + 1][3]);
;             const bf16x8 pb = __builtin_bit_cast(bf16x8, pw);
; #pragma unroll
;             for (int dt = 0; dt < 8; ++dt) { const LAS unsigned char* vr = lds + MA_VT + (32 * ks + 4 * fq + (fr >> 2)) * 288 + (16 * dt + 4 * (fr & 3)) * 2;
;                 const v4i16_t lo = vtr(vr), hi = vtr(vr + 16 * 288);
;                 ot[dt] = MFMA16(__builtin_shufflevector(lo, hi, 0, 1, 2, 3, 4, 5, 6, 7), pb, ot[dt]); } }
;         { const size_t m = (size_t)(m0 + 16 * w + fr); const float inv = 1.f / sm;
	v_add_f32_e32 v22, v59, v22
	v_exp_f32_e32 v55, v23
	v_sub_f32_e32 v23, v74, v150
	v_add_f32_e32 v22, v60, v22
	v_mul_f32_e32 v23, 0x3fb8aa3b, v23
	v_add_f32_e32 v22, v61, v22
	v_exp_f32_e32 v40, v23
	v_sub_f32_e32 v23, v75, v150
	v_add_f32_e32 v22, v62, v22
	v_mul_f32_e32 v23, 0x3fb8aa3b, v23
	v_add_f32_e32 v22, v63, v22
	v_exp_f32_e32 v42, v23
	v_sub_f32_e32 v23, v76, v150
	v_add_f32_e32 v22, v48, v22
	v_mul_f32_e32 v23, 0x3fb8aa3b, v23
	v_add_f32_e32 v22, v49, v22
	v_exp_f32_e32 v41, v23
	v_sub_f32_e32 v23, v77, v150
	v_add_f32_e32 v22, v50, v22
	v_mul_f32_e32 v23, 0x3fb8aa3b, v23
	v_add_f32_e32 v22, v52, v22
	v_exp_f32_e32 v44, v23
	v_sub_f32_e32 v23, v78, v150
	v_add_f32_e32 v22, v51, v22
	v_mul_f32_e32 v23, 0x3fb8aa3b, v23
	v_add_f32_e32 v22, v54, v22
	v_exp_f32_e32 v43, v23
	v_sub_f32_e32 v23, v79, v150
	v_add_f32_e32 v22, v53, v22
	v_mul_f32_e32 v23, 0x3fb8aa3b, v23
	v_add_f32_e32 v22, v55, v22
	v_exp_f32_e32 v46, v23
	v_sub_f32_e32 v23, v80, v150
	v_add_f32_e32 v22, v40, v22
	v_mul_f32_e32 v23, 0x3fb8aa3b, v23
	v_add_f32_e32 v22, v42, v22
	v_exp_f32_e32 v45, v23
	v_sub_f32_e32 v23, v81, v150
	v_add_f32_e32 v22, v41, v22
	v_mul_f32_e32 v23, 0x3fb8aa3b, v23
	v_add_f32_e32 v22, v44, v22
	v_exp_f32_e32 v47, v23
	v_add_f32_e32 v22, v43, v22
	v_add_f32_e32 v22, v46, v22
	v_add_f32_e32 v22, v45, v22
	v_add_f32_e32 v23, v47, v22
	v_sub_f32_e32 v22, v82, v150
	v_mul_f32_e32 v22, 0x3fb8aa3b, v22
	v_sub_f32_e32 v24, v83, v150
	v_exp_f32_e32 v22, v22
	v_mul_f32_e32 v24, 0x3fb8aa3b, v24
	v_exp_f32_e32 v24, v24
	v_sub_f32_e32 v28, v85, v150
	v_add_f32_e32 v23, v22, v23
	v_mul_f32_e32 v28, 0x3fb8aa3b, v28
	v_add_f32_e32 v25, v24, v23
	v_sub_f32_e32 v23, v84, v150
	v_mul_f32_e32 v23, 0x3fb8aa3b, v23
	v_exp_f32_e32 v23, v23
	v_exp_f32_e32 v36, v28
	v_sub_f32_e32 v29, v87, v150
	v_mul_f32_e32 v29, 0x3fb8aa3b, v29
	v_add_f32_e32 v25, v23, v25
	v_add_f32_e32 v28, v36, v25
	v_sub_f32_e32 v25, v86, v150
	v_mul_f32_e32 v25, 0x3fb8aa3b, v25
	v_exp_f32_e32 v38, v29
	v_sub_f32_e32 v29, v88, v150
	v_exp_f32_e32 v25, v25
	v_mul_f32_e32 v29, 0x3fb8aa3b, v29
	v_exp_f32_e32 v37, v29
	v_sub_f32_e32 v29, v89, v150
	v_mul_f32_e32 v29, 0x3fb8aa3b, v29
	v_exp_f32_e32 v39, v29
	v_add_f32_e32 v28, v25, v28
	v_add_f32_e32 v28, v38, v28
	v_add_f32_e32 v28, v37, v28
	v_add_f32_e32 v29, v39, v28
	v_sub_f32_e32 v28, v90, v150
	v_mul_f32_e32 v28, 0x3fb8aa3b, v28
	v_sub_f32_e32 v30, v91, v150
	v_exp_f32_e32 v28, v28
	v_mul_f32_e32 v30, 0x3fb8aa3b, v30
	v_exp_f32_e32 v30, v30
	v_sub_f32_e32 v32, v93, v150
	v_add_f32_e32 v29, v28, v29
	v_mul_f32_e32 v32, 0x3fb8aa3b, v32
	v_add_f32_e32 v31, v30, v29
	v_sub_f32_e32 v29, v92, v150
	v_mul_f32_e32 v29, 0x3fb8aa3b, v29
	v_exp_f32_e32 v29, v29
	v_exp_f32_e32 v32, v32
	v_sub_f32_e32 v18, v18, v150
	v_mul_f32_e32 v18, 0x3fb8aa3b, v18
	v_add_f32_e32 v31, v29, v31
	v_add_f32_e32 v33, v32, v31
	v_exp_f32_e32 v31, v18
	v_sub_f32_e32 v19, v19, v150
	v_mul_f32_e32 v19, 0x3fb8aa3b, v19
	v_exp_f32_e32 v34, v19
	v_sub_f32_e32 v19, v20, v150
	v_mul_f32_e32 v19, 0x3fb8aa3b, v19
	v_add_f32_e32 v18, v31, v33
	v_exp_f32_e32 v33, v19
	v_sub_f32_e32 v19, v21, v150
	v_mul_f32_e32 v19, 0x3fb8aa3b, v19
	v_exp_f32_e32 v35, v19
	v_add_f32_e32 v18, v34, v18
	v_add_f32_e32 v18, v33, v18
	v_bfe_u32 v20, v186, 16, 1
	v_add_f32_e32 v18, v35, v18
	ds_bpermute_b32 v19, v26, v18
	v_bfe_u32 v21, v185, 16, 1
	v_add3_u32 v64, v185, v21, s33
	v_add3_u32 v65, v186, v20, s33
	v_bfe_u32 v20, v183, 16, 1
	v_bfe_u32 v21, v184, 16, 1
	s_waitcnt lgkmcnt(0)
	v_add_f32_e32 v26, v18, v19
	v_cvt_pk_bf16_f32 v21, v190, v191
	v_cvt_pk_bf16_f32 v20, v187, v188
	v_cvt_pk_bf16_f32 v19, v184, v186
	v_cvt_pk_bf16_f32 v18, v183, v185
	ds_read_b64_tr_b16 v[66:67], v128 offset:4608
	ds_read_b64_tr_b16 v[64:65], v128
	ds_read_b64_tr_b16 v[68:69], v128 offset:32
	ds_read_b64_tr_b16 v[70:71], v128 offset:4640
	ds_read_b64_tr_b16 v[72:73], v128 offset:64
	ds_read_b64_tr_b16 v[74:75], v128 offset:4672
	ds_read_b64_tr_b16 v[76:77], v128 offset:96
	ds_read_b64_tr_b16 v[78:79], v128 offset:4704
	ds_read_b64_tr_b16 v[80:81], v128 offset:128
	ds_read_b64_tr_b16 v[82:83], v128 offset:4736
	ds_read_b64_tr_b16 v[84:85], v128 offset:160
	ds_read_b64_tr_b16 v[86:87], v128 offset:4768
	ds_read_b64_tr_b16 v[88:89], v128 offset:192
	ds_read_b64_tr_b16 v[90:91], v128 offset:4800
	ds_read_b64_tr_b16 v[150:151], v128 offset:224
	ds_read_b64_tr_b16 v[152:153], v128 offset:4832
	s_waitcnt lgkmcnt(14)
	v_mfma_f32_16x16x32_bf16 v[64:67], v[64:67], v[18:21], 0
	v_bfe_u32 v92, v182, 16, 1
	v_bfe_u32 v93, v180, 16, 1
	v_add3_u32 v93, v180, v93, s33
	s_waitcnt lgkmcnt(12)
	v_mfma_f32_16x16x32_bf16 v[68:71], v[68:71], v[18:21], 0
	v_add3_u32 v92, v182, v92, s33
	ds_bpermute_b32 v27, v27, v26
	s_waitcnt lgkmcnt(0)
	v_add_f32_e32 v26, v26, v27
	v_mfma_f32_16x16x32_bf16 v[72:75], v[72:75], v[18:21], 0
	v_div_scale_f32 v27, s[0:1], v26, v26, 1.0
	v_mfma_f32_16x16x32_bf16 v[76:79], v[76:79], v[18:21], 0
	v_mfma_f32_16x16x32_bf16 v[80:83], v[80:83], v[18:21], 0
	v_mfma_f32_16x16x32_bf16 v[84:87], v[84:87], v[18:21], 0
	v_mfma_f32_16x16x32_bf16 v[88:91], v[88:91], v[18:21], 0
	v_mfma_f32_16x16x32_bf16 v[18:21], v[150:153], v[18:21], 0
	v_bfe_u32 v151, v176, 16, 1
	v_bfe_u32 v150, v178, 16, 1
	v_add3_u32 v176, v176, v151, s33
	v_bfe_u32 v151, v175, 16, 1
	v_bfe_u32 v152, v177, 16, 1
	v_add3_u32 v150, v178, v150, s33
	v_bfe_u32 v153, v179, 16, 1
	v_add3_u32 v152, v177, v152, s33
	v_add3_u32 v151, v175, v151, s33
	v_add3_u32 v153, v179, v153, s33
	v_lshrrev_b32_e32 v175, 16, v151
	v_lshrrev_b32_e32 v151, 16, v152
	v_lshrrev_b32_e32 v152, 16, v153
	v_and_or_b32 v151, v150, s11, v151
	v_and_or_b32 v150, v176, s11, v175
	ds_read_b64_tr_b16 v[176:177], v128 offset:9216
	ds_read_b64_tr_b16 v[178:179], v128 offset:13824
	v_cvt_pk_bf16_f32 v153, v181, v182
	v_and_or_b32 v152, v93, s11, v152
	v_bfe_u32 v93, v172, 16, 1
	v_add3_u32 v93, v172, v93, s33
	s_waitcnt lgkmcnt(0)
; #define LAS __attribute__((address_space(3)))
; __device__ __forceinline__ unsigned pk2(float lo, float hi) { return f2bf(lo) | (f2bf(hi) << 16); }
; #define MFMA16(a, b, c) __builtin_amdgcn_mfma_f32_16x16x32_bf16(a, b, c, 0, 0, 0)
; __device__ __forceinline__ v4i16_t vtr(const LAS unsigned char* p) { return __builtin_amdgcn_ds_read_tr16_b64_v4i16((LAS v4i16_t*)p); }
; __device__ __forceinline__ void memattn_group(const Params& p, LAS unsigned char* lds, int grp, const int tid) {
;     ...
; #pragma unroll
;         for (int ks = 0; ks < 8; ++ks) { v4u pw; pw.x = pk2(st[2 * ks][0], st[2 * ks][1]); pw.y = pk2(st[2 * ks][2], st[2 * ks][3]); pw.z = pk2(st[2 * ks + 1][0], st[2 * ks + 1][1]); pw.w = pk2(st[2 * ks + 1][2], st[2 * ks + 1][3]);
;             const bf16x8 pb = __builtin_bit_cast(bf16x8, pw);
; #pragma unroll
;             for (int dt = 0; dt < 8; ++dt) { const LAS unsigned char* vr = lds + MA_VT + (32 * ks + 4 * fq + (fr >> 2)) * 288 + (16 * dt + 4 * (fr & 3)) * 2;
;                 const v4i16_t lo = vtr(vr), hi = vtr(vr + 16 * 288);
;                 ot[dt] = MFMA16(__builtin_shufflevector(lo, hi, 0, 1, 2, 3, 4, 5, 6, 7), pb, ot[dt]); } }
	v_mfma_f32_16x16x32_bf16 v[64:67], v[176:179], v[150:153], v[64:67]
	ds_read_b64_tr_b16 v[176:177], v128 offset:9248
	ds_read_b64_tr_b16 v[178:179], v128 offset:13856
	v_bfe_u32 v92, v174, 16, 1
	v_add3_u32 v92, v174, v92, s33
	s_waitcnt lgkmcnt(0)
	v_mfma_f32_16x16x32_bf16 v[68:71], v[176:179], v[150:153], v[68:71]
	ds_read_b64_tr_b16 v[176:177], v128 offset:9280
	ds_read_b64_tr_b16 v[178:179], v128 offset:13888
	s_waitcnt lgkmcnt(0)
	v_mfma_f32_16x16x32_bf16 v[72:75], v[176:179], v[150:153], v[72:75]
	ds_read_b64_tr_b16 v[176:177], v128 offset:9312
	ds_read_b64_tr_b16 v[178:179], v128 offset:13920
	s_waitcnt lgkmcnt(0)
	v_mfma_f32_16x16x32_bf16 v[76:79], v[176:179], v[150:153], v[76:79]
	ds_read_b64_tr_b16 v[176:177], v128 offset:9344
	ds_read_b64_tr_b16 v[178:179], v128 offset:13952
	s_waitcnt lgkmcnt(0)
	v_mfma_f32_16x16x32_bf16 v[80:83], v[176:179], v[150:153], v[80:83]
	ds_read_b64_tr_b16 v[176:177], v128 offset:9376
	ds_read_b64_tr_b16 v[178:179], v128 offset:13984
	s_waitcnt lgkmcnt(0)
	v_mfma_f32_16x16x32_bf16 v[84:87], v[176:179], v[150:153], v[84:87]
	ds_read_b64_tr_b16 v[176:177], v128 offset:9408
	ds_read_b64_tr_b16 v[178:179], v128 offset:14016
	s_waitcnt lgkmcnt(0)
	v_mfma_f32_16x16x32_bf16 v[88:91], v[176:179], v[150:153], v[88:91]
	ds_read_b64_tr_b16 v[176:177], v128 offset:9440
	ds_read_b64_tr_b16 v[178:179], v128 offset:14048
	s_waitcnt lgkmcnt(0)
	v_mfma_f32_16x16x32_bf16 v[18:21], v[176:179], v[150:153], v[18:21]
	v_bfe_u32 v150, v170, 16, 1
	v_add3_u32 v150, v170, v150, s33
	v_bfe_u32 v170, v173, 16, 1
	v_bfe_u32 v152, v123, 16, 1
	v_bfe_u32 v153, v171, 16, 1
	v_add3_u32 v170, v173, v170, s33
	v_add3_u32 v153, v171, v153, s33
	v_add3_u32 v123, v123, v152, s33
	v_lshrrev_b32_e32 v152, 16, v170
	ds_read_b64_tr_b16 v[170:171], v128 offset:18432
	ds_read_b64_tr_b16 v[172:173], v128 offset:23040
	v_lshrrev_b32_e32 v123, 16, v123
	v_lshrrev_b32_e32 v151, 16, v153
	v_and_or_b32 v153, v92, s11, v152
	v_and_or_b32 v152, v93, s11, v151
	v_and_or_b32 v151, v150, s11, v123
	v_cvt_pk_bf16_f32 v150, v115, v117
	v_bfe_u32 v92, v63, 16, 1
	v_bfe_u32 v93, v61, 16, 1
	s_waitcnt lgkmcnt(0)
	v_mfma_f32_16x16x32_bf16 v[64:67], v[170:173], v[150:153], v[64:67]
	ds_read_b64_tr_b16 v[170:171], v128 offset:18464
	ds_read_b64_tr_b16 v[172:173], v128 offset:23072
	v_bfe_u32 v115, v59, 16, 1
	v_bfe_u32 v117, v57, 16, 1
	s_waitcnt lgkmcnt(0)
	v_mfma_f32_16x16x32_bf16 v[68:71], v[170:173], v[150:153], v[68:71]
	ds_read_b64_tr_b16 v[170:171], v128 offset:18496
	ds_read_b64_tr_b16 v[172:173], v128 offset:23104
	v_add3_u32 v117, v57, v117, s33
	v_add3_u32 v57, v59, v115, s33
	s_waitcnt lgkmcnt(0)
	v_mfma_f32_16x16x32_bf16 v[72:75], v[170:173], v[150:153], v[72:75]
	ds_read_b64_tr_b16 v[170:171], v128 offset:18528
	ds_read_b64_tr_b16 v[172:173], v128 offset:23136
	v_add3_u32 v61, v61, v93, s33
	v_add3_u32 v59, v63, v92, s33
	s_waitcnt lgkmcnt(0)
	v_mfma_f32_16x16x32_bf16 v[76:79], v[170:173], v[150:153], v[76:79]
	ds_read_b64_tr_b16 v[170:171], v128 offset:18560
	ds_read_b64_tr_b16 v[172:173], v128 offset:23168
	v_bfe_u32 v92, v58, 16, 1
	v_bfe_u32 v93, v60, 16, 1
	s_waitcnt lgkmcnt(0)
	v_mfma_f32_16x16x32_bf16 v[80:83], v[170:173], v[150:153], v[80:83]
	ds_read_b64_tr_b16 v[170:171], v128 offset:18592
	ds_read_b64_tr_b16 v[172:173], v128 offset:23200
	v_bfe_u32 v115, v62, 16, 1
	v_bfe_u32 v63, v56, 16, 1
	s_waitcnt lgkmcnt(0)
	v_mfma_f32_16x16x32_bf16 v[84:87], v[170:173], v[150:153], v[84:87]
	ds_read_b64_tr_b16 v[170:171], v128 offset:18624
	ds_read_b64_tr_b16 v[172:173], v128 offset:23232
	v_add3_u32 v62, v62, v115, s33
	v_add3_u32 v60, v60, v93, s33
	v_add3_u32 v58, v58, v92, s33
	v_add3_u32 v56, v56, v63, s33
	v_lshrrev_b32_e32 v63, 16, v58
	v_lshrrev_b32_e32 v58, 16, v60
	v_lshrrev_b32_e32 v60, 16, v62
	s_waitcnt lgkmcnt(0)
	v_mfma_f32_16x16x32_bf16 v[88:91], v[170:173], v[150:153], v[88:91]
	ds_read_b64_tr_b16 v[170:171], v128 offset:18656
	ds_read_b64_tr_b16 v[172:173], v128 offset:23264
	v_and_or_b32 v59, v59, s11, v60
	v_and_or_b32 v58, v61, s11, v58
	v_and_or_b32 v57, v57, s11, v63
	ds_read_b64_tr_b16 v[60:61], v128 offset:27648
	ds_read_b64_tr_b16 v[62:63], v128 offset:32256
	v_lshrrev_b32_e32 v56, 16, v56
	v_and_or_b32 v56, v117, s11, v56
	s_waitcnt lgkmcnt(2)
	v_mfma_f32_16x16x32_bf16 v[18:21], v[170:173], v[150:153], v[18:21]
	v_ashrrev_i32_e32 v123, 31, v122
	s_waitcnt lgkmcnt(0)
	v_mfma_f32_16x16x32_bf16 v[60:63], v[60:63], v[56:59], v[64:67]
	s_nop 2
	ds_read_b64_tr_b16 v[64:65], v128 offset:27680
	ds_read_b64_tr_b16 v[66:67], v128 offset:32288
	s_waitcnt lgkmcnt(0)
	v_mfma_f32_16x16x32_bf16 v[64:67], v[64:67], v[56:59], v[68:71]
	s_nop 2
	ds_read_b64_tr_b16 v[68:69], v128 offset:27712
	ds_read_b64_tr_b16 v[70:71], v128 offset:32320
	s_waitcnt lgkmcnt(0)
	v_mfma_f32_16x16x32_bf16 v[68:71], v[68:71], v[56:59], v[72:75]
	s_nop 2
	ds_read_b64_tr_b16 v[72:73], v128 offset:27744
	ds_read_b64_tr_b16 v[74:75], v128 offset:32352
	s_waitcnt lgkmcnt(0)
	v_mfma_f32_16x16x32_bf16 v[72:75], v[72:75], v[56:59], v[76:79]
	s_nop 2
	ds_read_b64_tr_b16 v[76:77], v128 offset:27776
	ds_read_b64_tr_b16 v[78:79], v128 offset:32384
	s_waitcnt lgkmcnt(0)
	v_mfma_f32_16x16x32_bf16 v[76:79], v[76:79], v[56:59], v[80:83]
	s_nop 2
	ds_read_b64_tr_b16 v[80:81], v128 offset:27808
	ds_read_b64_tr_b16 v[82:83], v128 offset:32416
	s_waitcnt lgkmcnt(0)
	v_mfma_f32_16x16x32_bf16 v[80:83], v[80:83], v[56:59], v[84:87]
	s_nop 2
	ds_read_b64_tr_b16 v[84:85], v128 offset:27840
	ds_read_b64_tr_b16 v[86:87], v128 offset:32448
	s_waitcnt lgkmcnt(0)
	v_mfma_f32_16x16x32_bf16 v[84:87], v[84:87], v[56:59], v[88:91]
	s_nop 2
	ds_read_b64_tr_b16 v[88:89], v128 offset:27872
	ds_read_b64_tr_b16 v[90:91], v128 offset:32480
	s_waitcnt lgkmcnt(0)
; #define LAS __attribute__((address_space(3)))
; __device__ __forceinline__ unsigned pk2(float lo, float hi) { return f2bf(lo) | (f2bf(hi) << 16); }
; #define MFMA16(a, b, c) __builtin_amdgcn_mfma_f32_16x16x32_bf16(a, b, c, 0, 0, 0)
; __device__ __forceinline__ v4i16_t vtr(const LAS unsigned char* p) { return __builtin_amdgcn_ds_read_tr16_b64_v4i16((LAS v4i16_t*)p); }
; __device__ __forceinline__ void memattn_group(const Params& p, LAS unsigned char* lds, int grp, const int tid) {
;     ...
; #pragma unroll
;         for (int ks = 0; ks < 8; ++ks) { v4u pw; pw.x = pk2(st[2 * ks][0], st[2 * ks][1]); pw.y = pk2(st[2 * ks][2], st[2 * ks][3]); pw.z = pk2(st[2 * ks + 1][0], st[2 * ks + 1][1]); pw.w = pk2(st[2 * ks + 1][2], st[2 * ks + 1][3]);
;             const bf16x8 pb = __builtin_bit_cast(bf16x8, pw);
; #pragma unroll
;             for (int dt = 0; dt < 8; ++dt) { const LAS unsigned char* vr = lds + MA_VT + (32 * ks + 4 * fq + (fr >> 2)) * 288 + (16 * dt + 4 * (fr & 3)) * 2;
;                 const v4i16_t lo = vtr(vr), hi = vtr(vr + 16 * 288);
;                 ot[dt] = MFMA16(__builtin_shufflevector(lo, hi, 0, 1, 2, 3, 4, 5, 6, 7), pb, ot[dt]); } }
	v_mfma_f32_16x16x32_bf16 v[18:21], v[88:91], v[56:59], v[18:21]
	v_bfe_u32 v56, v55, 16, 1
	v_bfe_u32 v57, v54, 16, 1
	v_bfe_u32 v58, v52, 16, 1
	v_bfe_u32 v59, v49, 16, 1
	v_add3_u32 v59, v49, v59, s33
	v_add3_u32 v49, v52, v58, s33
	v_add3_u32 v52, v54, v57, s33
	v_add3_u32 v54, v55, v56, s33
	v_bfe_u32 v55, v48, 16, 1
	v_bfe_u32 v56, v50, 16, 1
	v_bfe_u32 v57, v51, 16, 1
	v_bfe_u32 v58, v53, 16, 1
	v_add3_u32 v53, v53, v58, s33
	v_add3_u32 v51, v51, v57, s33
	v_add3_u32 v50, v50, v56, s33
	v_add3_u32 v48, v48, v55, s33
	v_lshrrev_b32_e32 v48, 16, v48
	v_lshrrev_b32_e32 v55, 16, v50
	v_lshrrev_b32_e32 v50, 16, v51
	v_lshrrev_b32_e32 v51, 16, v53
	v_and_or_b32 v51, v54, s11, v51
	v_and_or_b32 v50, v52, s11, v50
	v_and_or_b32 v49, v49, s11, v55
	v_and_or_b32 v48, v59, s11, v48
	ds_read_b64_tr_b16 v[52:53], v128 offset:36864
	ds_read_b64_tr_b16 v[54:55], v128 offset:41472
	ds_read_b64_tr_b16 v[56:57], v128 offset:36896
	ds_read_b64_tr_b16 v[58:59], v128 offset:41504
	s_waitcnt lgkmcnt(2)
	v_mfma_f32_16x16x32_bf16 v[52:55], v[52:55], v[48:51], v[60:63]
	s_nop 2
	ds_read_b64_tr_b16 v[60:61], v128 offset:36928
	ds_read_b64_tr_b16 v[62:63], v128 offset:41536
	s_waitcnt lgkmcnt(2)
	v_mfma_f32_16x16x32_bf16 v[56:59], v[56:59], v[48:51], v[64:67]
	s_nop 2
	ds_read_b64_tr_b16 v[64:65], v128 offset:36960
	ds_read_b64_tr_b16 v[66:67], v128 offset:41568
	s_waitcnt lgkmcnt(2)
	v_mfma_f32_16x16x32_bf16 v[60:63], v[60:63], v[48:51], v[68:71]
	s_nop 2
	ds_read_b64_tr_b16 v[68:69], v128 offset:36992
	ds_read_b64_tr_b16 v[70:71], v128 offset:41600
	s_waitcnt lgkmcnt(2)
	v_mfma_f32_16x16x32_bf16 v[64:67], v[64:67], v[48:51], v[72:75]
	s_nop 2
	ds_read_b64_tr_b16 v[72:73], v128 offset:37024
	ds_read_b64_tr_b16 v[74:75], v128 offset:41632
	s_waitcnt lgkmcnt(2)
	v_mfma_f32_16x16x32_bf16 v[68:71], v[68:71], v[48:51], v[76:79]
	s_nop 2
	ds_read_b64_tr_b16 v[76:77], v128 offset:37056
	ds_read_b64_tr_b16 v[78:79], v128 offset:41664
	s_waitcnt lgkmcnt(2)
	v_mfma_f32_16x16x32_bf16 v[72:75], v[72:75], v[48:51], v[80:83]
	s_nop 2
	ds_read_b64_tr_b16 v[80:81], v128 offset:37088
	ds_read_b64_tr_b16 v[82:83], v128 offset:41696
	s_waitcnt lgkmcnt(2)
	v_mfma_f32_16x16x32_bf16 v[76:79], v[76:79], v[48:51], v[84:87]
	s_waitcnt lgkmcnt(0)
	v_mfma_f32_16x16x32_bf16 v[18:21], v[80:83], v[48:51], v[18:21]
	v_bfe_u32 v48, v47, 16, 1
	v_bfe_u32 v49, v46, 16, 1
	v_bfe_u32 v50, v44, 16, 1
	v_bfe_u32 v51, v42, 16, 1
	v_add3_u32 v51, v42, v51, s33
	v_add3_u32 v42, v46, v49, s33
	v_add3_u32 v46, v47, v48, s33
	v_bfe_u32 v47, v40, 16, 1
	v_bfe_u32 v49, v43, 16, 1
	v_bfe_u32 v50, v45, 16, 1
	v_add3_u32 v45, v45, v50, s33
	v_add3_u32 v43, v43, v49, s33
	v_add3_u32 v40, v40, v47, s33
	v_lshrrev_b32_e32 v40, 16, v40
	v_lshrrev_b32_e32 v47, 16, v43
	v_lshrrev_b32_e32 v43, 16, v45
	v_and_or_b32 v43, v46, s11, v43
	v_and_or_b32 v42, v42, s11, v47
	v_cvt_pk_bf16_f32 v41, v41, v44
	v_and_or_b32 v40, v51, s11, v40
	ds_read_b64_tr_b16 v[44:45], v128 offset:46080
	ds_read_b64_tr_b16 v[46:47], v128 offset:50688
	ds_read_b64_tr_b16 v[48:49], v128 offset:46112
	ds_read_b64_tr_b16 v[50:51], v128 offset:50720
	s_waitcnt lgkmcnt(2)
	v_mfma_f32_16x16x32_bf16 v[44:47], v[44:47], v[40:43], v[52:55]
	s_nop 2
	ds_read_b64_tr_b16 v[52:53], v128 offset:46144
	ds_read_b64_tr_b16 v[54:55], v128 offset:50752
	s_waitcnt lgkmcnt(2)
	v_mfma_f32_16x16x32_bf16 v[48:51], v[48:51], v[40:43], v[56:59]
	s_nop 2
	ds_read_b64_tr_b16 v[56:57], v128 offset:46176
	ds_read_b64_tr_b16 v[58:59], v128 offset:50784
	s_waitcnt lgkmcnt(2)
	v_mfma_f32_16x16x32_bf16 v[52:55], v[52:55], v[40:43], v[60:63]
	s_nop 2
	ds_read_b64_tr_b16 v[60:61], v128 offset:46208
	ds_read_b64_tr_b16 v[62:63], v128 offset:50816
	s_waitcnt lgkmcnt(2)
	v_mfma_f32_16x16x32_bf16 v[56:59], v[56:59], v[40:43], v[64:67]
	s_nop 2
	ds_read_b64_tr_b16 v[64:65], v128 offset:46240
	ds_read_b64_tr_b16 v[66:67], v128 offset:50848
	s_waitcnt lgkmcnt(2)
	v_mfma_f32_16x16x32_bf16 v[60:63], v[60:63], v[40:43], v[68:71]
	s_nop 2
	ds_read_b64_tr_b16 v[68:69], v128 offset:46272
	ds_read_b64_tr_b16 v[70:71], v128 offset:50880
	s_waitcnt lgkmcnt(2)
	v_mfma_f32_16x16x32_bf16 v[64:67], v[64:67], v[40:43], v[72:75]
	s_nop 2
	ds_read_b64_tr_b16 v[72:73], v128 offset:46304
	ds_read_b64_tr_b16 v[74:75], v128 offset:50912
	s_waitcnt lgkmcnt(2)
	v_mfma_f32_16x16x32_bf16 v[68:71], v[68:71], v[40:43], v[76:79]
	s_waitcnt lgkmcnt(0)
	v_mfma_f32_16x16x32_bf16 v[40:43], v[72:75], v[40:43], v[18:21]
	s_nop 2
	v_bfe_u32 v18, v39, 16, 1
	v_bfe_u32 v19, v38, 16, 1
	v_bfe_u32 v20, v36, 16, 1
	v_bfe_u32 v21, v24, 16, 1
	v_add3_u32 v21, v24, v21, s33
	v_add3_u32 v20, v36, v20, s33
	v_add3_u32 v19, v38, v19, s33
	v_add3_u32 v18, v39, v18, s33
	v_bfe_u32 v24, v22, 16, 1
	v_bfe_u32 v36, v23, 16, 1
	v_bfe_u32 v38, v25, 16, 1
	v_bfe_u32 v39, v37, 16, 1
	v_add3_u32 v37, v37, v39, s33
	v_add3_u32 v25, v25, v38, s33
	v_add3_u32 v23, v23, v36, s33
	v_add3_u32 v22, v22, v24, s33
	v_lshrrev_b32_e32 v22, 16, v22
	v_lshrrev_b32_e32 v23, 16, v23
	v_lshrrev_b32_e32 v24, 16, v25
	v_lshrrev_b32_e32 v25, 16, v37
	v_and_or_b32 v39, v18, s11, v25
	v_and_or_b32 v38, v19, s11, v24
	v_and_or_b32 v37, v20, s11, v23
	v_and_or_b32 v36, v21, s11, v22
	ds_read_b64_tr_b16 v[18:19], v128 offset:55296
	ds_read_b64_tr_b16 v[20:21], v128 offset:59904
	s_waitcnt lgkmcnt(0)
	v_mfma_f32_16x16x32_bf16 v[44:47], v[18:21], v[36:39], v[44:47]
	ds_read_b64_tr_b16 v[18:19], v128 offset:55328
	ds_read_b64_tr_b16 v[20:21], v128 offset:59936
	s_waitcnt lgkmcnt(0)
	v_mfma_f32_16x16x32_bf16 v[48:51], v[18:21], v[36:39], v[48:51]
	ds_read_b64_tr_b16 v[18:19], v128 offset:55360
	ds_read_b64_tr_b16 v[20:21], v128 offset:59968
	s_waitcnt lgkmcnt(0)
; #define LAS __attribute__((address_space(3)))
; __device__ __forceinline__ unsigned pk2(float lo, float hi) { return f2bf(lo) | (f2bf(hi) << 16); }
; #define MFMA16(a, b, c) __builtin_amdgcn_mfma_f32_16x16x32_bf16(a, b, c, 0, 0, 0)
; __device__ __forceinline__ v4i16_t vtr(const LAS unsigned char* p) { return __builtin_amdgcn_ds_read_tr16_b64_v4i16((LAS v4i16_t*)p); }
; __device__ __forceinline__ void memattn_group(const Params& p, LAS unsigned char* lds, int grp, const int tid) {
;     ...
;         bf16x8 qa[4];
; #pragma unroll
;         for (int ks = 0; ks < 4; ++ks) qa[ks] = qn[ks];
;         if (j < 3) { const bf16* qp = QM + (size_t)(m0 + 128 + 16 * w + fr) * 512 + h * 128 + 8 * fq;
; #pragma unroll
;             for (int ks = 0; ks < 4; ++ks) qn[ks] = *(const bf16x8*)(qp + 32 * ks); }
;     ...
; #pragma unroll
;         for (int ks = 0; ks < 8; ++ks) { v4u pw; pw.x = pk2(st[2 * ks][0], st[2 * ks][1]); pw.y = pk2(st[2 * ks][2], st[2 * ks][3]); pw.z = pk2(st[2 * ks + 1][0], st[2 * ks + 1][1]); pw.w = pk2(st[2 * ks + 1][2], st[2 * ks + 1][3]);
;             const bf16x8 pb = __builtin_bit_cast(bf16x8, pw);
; #pragma unroll
;             for (int dt = 0; dt < 8; ++dt) { const LAS unsigned char* vr = lds + MA_VT + (32 * ks + 4 * fq + (fr >> 2)) * 288 + (16 * dt + 4 * (fr & 3)) * 2;
;                 const v4i16_t lo = vtr(vr), hi = vtr(vr + 16 * 288);
;                 ot[dt] = MFMA16(__builtin_shufflevector(lo, hi, 0, 1, 2, 3, 4, 5, 6, 7), pb, ot[dt]); } }
;         { const size_t m = (size_t)(m0 + 16 * w + fr); const float inv = 1.f / sm;
; #pragma unroll
;           for (int dt = 0; dt < 8; ++dt) { unsigned long long wv = (unsigned long long)pk2(ot[dt][0] * inv, ot[dt][1] * inv) | ((unsigned long long)pk2(ot[dt][2] * inv, ot[dt][3] * inv) << 32);
;               *(unsigned long long*)(QM + m * 512 + h * 128 + 16 * dt + 4 * fq) = wv; } }
	v_mfma_f32_16x16x32_bf16 v[52:55], v[18:21], v[36:39], v[52:55]
	ds_read_b64_tr_b16 v[18:19], v128 offset:55392
	ds_read_b64_tr_b16 v[20:21], v128 offset:60000
	s_waitcnt lgkmcnt(0)
	v_mfma_f32_16x16x32_bf16 v[56:59], v[18:21], v[36:39], v[56:59]
	ds_read_b64_tr_b16 v[18:19], v128 offset:55424
	ds_read_b64_tr_b16 v[20:21], v128 offset:60032
	ds_read_b64_tr_b16 v[22:23], v128 offset:55456
	ds_read_b64_tr_b16 v[24:25], v128 offset:60064
	s_waitcnt lgkmcnt(2)
	v_mfma_f32_16x16x32_bf16 v[18:21], v[18:21], v[36:39], v[60:63]
	s_waitcnt lgkmcnt(0)
	v_mfma_f32_16x16x32_bf16 v[60:63], v[22:25], v[36:39], v[64:67]
	ds_read_b64_tr_b16 v[22:23], v128 offset:55488
	ds_read_b64_tr_b16 v[24:25], v128 offset:60096
	s_nop 0
	ds_read_b64_tr_b16 v[64:65], v128 offset:55520
	ds_read_b64_tr_b16 v[66:67], v128 offset:60128
	s_waitcnt lgkmcnt(2)
	v_mfma_f32_16x16x32_bf16 v[22:25], v[22:25], v[36:39], v[68:71]
	s_waitcnt lgkmcnt(0)
	v_mfma_f32_16x16x32_bf16 v[36:39], v[64:67], v[36:39], v[40:43]
	s_nop 2
	v_bfe_u32 v40, v35, 16, 1
	v_bfe_u32 v41, v34, 16, 1
	v_bfe_u32 v42, v32, 16, 1
	v_bfe_u32 v43, v30, 16, 1
	v_add3_u32 v43, v30, v43, s33
	v_add3_u32 v30, v34, v41, s33
	v_add3_u32 v34, v35, v40, s33
	v_bfe_u32 v41, v31, 16, 1
	v_bfe_u32 v42, v33, 16, 1
	v_bfe_u32 v35, v28, 16, 1
	v_add3_u32 v33, v33, v42, s33
	v_add3_u32 v31, v31, v41, s33
	v_add3_u32 v28, v28, v35, s33
	v_lshrrev_b32_e32 v35, 16, v31
	v_lshrrev_b32_e32 v31, 16, v33
	v_and_or_b32 v31, v34, s11, v31
	v_and_or_b32 v30, v30, s11, v35
	v_cvt_pk_bf16_f32 v29, v29, v32
	ds_read_b64_tr_b16 v[32:33], v128 offset:64512
	ds_read_b64_tr_b16 v[34:35], v129
	v_lshrrev_b32_e32 v28, 16, v28
	v_and_or_b32 v28, v43, s11, v28
	ds_read_b64_tr_b16 v[40:41], v128 offset:64544
	ds_read_b64_tr_b16 v[42:43], v130
	s_waitcnt lgkmcnt(2)
	v_mfma_f32_16x16x32_bf16 v[32:35], v[32:35], v[28:31], v[44:47]
	s_nop 2
	ds_read_b64_tr_b16 v[44:45], v128 offset:64576
	ds_read_b64_tr_b16 v[46:47], v131
	s_waitcnt lgkmcnt(2)
	v_mfma_f32_16x16x32_bf16 v[40:43], v[40:43], v[28:31], v[48:51]
	s_nop 2
	ds_read_b64_tr_b16 v[48:49], v128 offset:64608
	ds_read_b64_tr_b16 v[50:51], v132
	s_waitcnt lgkmcnt(2)
	v_mfma_f32_16x16x32_bf16 v[44:47], v[44:47], v[28:31], v[52:55]
	s_nop 2
	ds_read_b64_tr_b16 v[52:53], v128 offset:64640
	ds_read_b64_tr_b16 v[54:55], v133
	s_waitcnt lgkmcnt(2)
	v_mfma_f32_16x16x32_bf16 v[48:51], v[48:51], v[28:31], v[56:59]
	s_waitcnt lgkmcnt(0)
	v_mfma_f32_16x16x32_bf16 v[18:21], v[52:55], v[28:31], v[18:21]
	ds_read_b64_tr_b16 v[52:53], v128 offset:64672
	ds_read_b64_tr_b16 v[54:55], v134
	ds_read_b64_tr_b16 v[56:57], v128 offset:64704
	ds_read_b64_tr_b16 v[58:59], v135
	s_waitcnt lgkmcnt(0)
	v_mfma_f32_16x16x32_bf16 v[22:25], v[56:59], v[28:31], v[22:25]
	ds_read_b64_tr_b16 v[56:57], v128 offset:64736
	ds_read_b64_tr_b16 v[58:59], v136
	v_mfma_f32_16x16x32_bf16 v[52:55], v[52:55], v[28:31], v[60:63]
	s_waitcnt lgkmcnt(0)
	v_mfma_f32_16x16x32_bf16 v[28:31], v[56:59], v[28:31], v[36:39]
	s_nop 2
	v_rcp_f32_e32 v36, v27
	s_nop 0
	v_fma_f32 v37, -v27, v36, 1.0
	v_fmac_f32_e32 v36, v37, v36
	v_div_scale_f32 v37, vcc, 1.0, v26, 1.0
	v_mul_f32_e32 v38, v37, v36
	v_fma_f32 v39, -v27, v38, v37
	v_fmac_f32_e32 v38, v39, v36
	v_fma_f32 v27, -v27, v38, v37
	v_div_fmas_f32 v27, v27, v36, v38
	v_div_fixup_f32 v36, v27, v26, 1.0
	v_mul_f32_e32 v32, v36, v32
	v_mul_f32_e32 v33, v36, v33
	v_bfe_u32 v37, v32, 16, 1
	v_add3_u32 v32, v32, v37, s33
	v_bfe_u32 v37, v33, 16, 1
	v_lshrrev_b32_e32 v32, 16, v32
	v_add3_u32 v33, v33, v37, s33
	v_and_or_b32 v32, v33, s11, v32
	v_mul_f32_e32 v33, v36, v34
	v_mul_f32_e32 v34, v36, v35
	v_lshlrev_b64 v[26:27], 10, v[122:123]
	v_lshl_add_u64 v[26:27], v[120:121], 0, v[26:27]
	v_cvt_pk_bf16_f32 v33, v33, v34
	global_store_dwordx2 v[26:27], v[32:33], off
	v_mul_f32_e32 v32, v36, v40
	v_mul_f32_e32 v33, v36, v41
	v_cvt_pk_bf16_f32 v32, v32, v33
	v_mul_f32_e32 v33, v36, v42
	v_mul_f32_e32 v34, v36, v43
	v_cvt_pk_bf16_f32 v33, v33, v34
	global_store_dwordx2 v[26:27], v[32:33], off offset:32
	v_mul_f32_e32 v32, v36, v44
	v_mul_f32_e32 v33, v36, v45
	v_cvt_pk_bf16_f32 v32, v32, v33
	v_mul_f32_e32 v33, v36, v46
	v_mul_f32_e32 v34, v36, v47
	v_cvt_pk_bf16_f32 v33, v33, v34
	global_store_dwordx2 v[26:27], v[32:33], off offset:64
	v_mul_f32_e32 v32, v36, v48
	v_mul_f32_e32 v33, v36, v49
	v_cvt_pk_bf16_f32 v32, v32, v33
	v_mul_f32_e32 v33, v36, v50
	v_mul_f32_e32 v34, v36, v51
	v_bfe_u32 v35, v33, 16, 1
	v_add3_u32 v33, v33, v35, s33
	v_bfe_u32 v35, v34, 16, 1
	v_lshrrev_b32_e32 v33, 16, v33
	v_add3_u32 v34, v34, v35, s33
	v_and_or_b32 v33, v34, s11, v33
	v_mul_f32_e32 v18, v36, v18
	global_store_dwordx2 v[26:27], v[32:33], off offset:96
	v_mul_f32_e32 v19, v36, v19
	v_cvt_pk_bf16_f32 v18, v18, v19
	v_mul_f32_e32 v19, v36, v20
	v_mul_f32_e32 v20, v36, v21
	v_cvt_pk_bf16_f32 v19, v19, v20
	global_store_dwordx2 v[26:27], v[18:19], off offset:128
	v_mul_f32_e32 v18, v36, v52
	v_mul_f32_e32 v19, v36, v53
	v_cvt_pk_bf16_f32 v18, v18, v19
	v_mul_f32_e32 v19, v36, v54
	v_mul_f32_e32 v20, v36, v55
	v_cvt_pk_bf16_f32 v19, v19, v20
	global_store_dwordx2 v[26:27], v[18:19], off offset:160
	v_mul_f32_e32 v18, v36, v22
	v_mul_f32_e32 v19, v36, v23
	v_cvt_pk_bf16_f32 v18, v18, v19
	v_mul_f32_e32 v19, v36, v24
	v_mul_f32_e32 v20, v36, v25
	v_cvt_pk_bf16_f32 v19, v19, v20
	global_store_dwordx2 v[26:27], v[18:19], off offset:192
	v_mul_f32_e32 v18, v36, v28
	v_mul_f32_e32 v19, v36, v29
	v_cvt_pk_bf16_f32 v18, v18, v19
	v_mul_f32_e32 v19, v36, v30
	v_mul_f32_e32 v20, v36, v31
	v_cvt_pk_bf16_f32 v19, v19, v20
	global_store_dwordx2 v[26:27], v[18:19], off offset:224
	s_waitcnt vmcnt(8)
	v_mov_b64_e32 v[32:33], v[8:9]
	v_mov_b64_e32 v[28:29], v[12:13]
	v_mov_b64_e32 v[24:25], v[16:17]
	v_mov_b64_e32 v[20:21], v[4:5]
	v_mov_b64_e32 v[30:31], v[6:7]
	v_mov_b64_e32 v[26:27], v[10:11]
	v_mov_b64_e32 v[22:23], v[14:15]
	v_mov_b64_e32 v[18:19], v[2:3]
	s_cbranch_scc0 .LBB0_494
